# MLA loop: K/V tile pointers kept as 64-bit addresses (11 fewer VALU per tile), PV MFMAs spread through the softmax VALU
# speedup vs baseline: 1.3065x; 1.0072x over previous
; #define GLOAD(t) { const int pos0_ = TILE_POS(t); \
;     rk0 = *(const uint4*)(K + (size_t)(pos0_ + kr0) * ldk + kc0); rk1 = *(const uint4*)(K + (size_t)(pos0_ + kr1) * ldk + kc1); \
;     if (NKC == 3) rk2 = *(const uint4*)(K + (size_t)(pos0_ + kr2) * ldk + kc2); \
;     rv0 = *(const uint4*)(Vt + (size_t)vd0 * SEQA + pos0_ + vk0); rv1 = *(const uint4*)(Vt + (size_t)(vd0 + 32) * SEQA + pos0_ + vk0); }
; #define LSTORE(bf) { *(uint4*)&Ks[bf][kr0][kc0] = rk0; *(uint4*)&Ks[bf][kr1][kc1] = rk1; if (NKC == 3) *(uint4*)&Ks[bf][kr2][kc2] = rk2; \
;     *(uint2*)&Vs[bf][vd0][vk0] = make_uint2(rv0.x, rv0.y); *(uint2*)&Vs[bf][vd0][vk0 + 4] = make_uint2(rv0.z, rv0.w); \
;     *(uint2*)&Vs[bf][vd0 + 32][vk0] = make_uint2(rv1.x, rv1.y); *(uint2*)&Vs[bf][vd0 + 32][vk0 + 4] = make_uint2(rv1.z, rv1.w); }
; #define GLOAD(t) { const int pos0_ = (t) * 64; \
;     rk0 = *(const uint4*)(K + (size_t)(pos0_ + kr0) * ldk + kc0); rk1 = *(const uint4*)(K + (size_t)(pos0_ + kr1) * ldk + kc1); \
;     if (NKC == 3) rk2 = *(const uint4*)(K + (size_t)(pos0_ + kr2) * ldk + kc2); \
;     rv0 = *(const uint4*)(Vt + (size_t)vd0 * SEQA + pos0_ + vk0); rv1 = *(const uint4*)(Vt + (size_t)(vd0 + 32) * SEQA + pos0_ + vk0); }
; #define LSTORE(bf) { *(uint4*)&Ks[bf][kr0][kc0] = rk0; *(uint4*)&Ks[bf][kr1][kc1] = rk1; if (NKC == 3) *(uint4*)&Ks[bf][kr2][kc2] = rk2; \
;     *(uint2*)&Vs[bf][vd0][vk0] = make_uint2(rv0.x, rv0.y); *(uint2*)&Vs[bf][vd0][vk0 + 4] = make_uint2(rv0.z, rv0.w); \
;     *(uint2*)&Vs[bf][vd0 + 32][vk0] = make_uint2(rv1.x, rv1.y); *(uint2*)&Vs[bf][vd0 + 32][vk0 + 4] = make_uint2(rv1.z, rv1.w); }
; template <int DK, bool NA> ...
;     ...
;   const int kr0 = tid / KCH, kc0 = (tid % KCH) * 8, kr1 = (tid + 256) / KCH, kc1 = ((tid + 256) % KCH) * 8, kr2 = (tid + 512) / KCH, kc2 = ((tid + 512) % KCH) * 8;
;   const int vd0 = tid >> 3, vk0 = (tid & 7) * 8;
;     ...
;   GLOAD(0); LSTORE(0);
;   __syncthreads();
.LBB0_889:
	v_cmp_gt_i32_e32 vcc, s11, v0
	s_and_saveexec_b64 s[2:3], vcc
	s_xor_b64 s[2:3], exec, s[2:3]
	v_ashrrev_i32_e32 v2, 7, v0
	s_or_saveexec_b64 s[6:7], s[2:3]
	v_mov_b64_e32 v[4:5], 0x100
	v_mov_b32_e32 v5, 0x42
	v_mov_b32_e32 v3, 31
	v_mov_b32_e32 v6, 5
	s_mov_b64 s[12:13], 0x3000
	s_xor_b64 exec, exec, s[6:7]
	v_add_u32_e32 v2, 0xfffffc00, v0
	v_mov_b64_e32 v[4:5], 0
	v_lshrrev_b32_e32 v2, 3, v2
	v_mov_b32_e32 v5, 2
	v_mov_b32_e32 v6, 1
	v_mov_b32_e32 v3, 1
	s_or_b64 exec, exec, s[6:7]
	v_and_b32_e32 v7, v3, v0
	v_ashrrev_i32_e32 v3, 31, v2
	v_bfe_u32 v147, v0, v6, 2
	v_lshl_add_u32 v0, v7, 7, v4
	s_movk_i32 s2, 0x1100
	v_lshlrev_b64 v[8:9], 2, v[2:3]
	v_mad_i64_i32 v[158:159], s[2:3], v2, s2, v[0:1]
	v_or_b32_e32 v0, v8, v147
	v_mov_b64_e32 v[10:11], s[36:37]
	v_mad_u64_u32 v[18:19], s[2:3], v0, s48, v[10:11]
	v_mov_b64_e32 v[10:11], s[38:39]
	v_mov_b64_e32 v[6:7], s[34:35]
	v_mad_i32_i24 v19, v9, s48, v19
	v_mad_u64_u32 v[20:21], s[2:3], v0, s14, v[10:11]
	v_mad_i32_i24 v21, v9, s14, v21
	v_lshl_add_u64 v[8:9], v[18:19], 0, v[120:121]
	v_lshl_add_u64 v[10:11], v[18:19], 0, v[122:123]
	v_mad_u64_u32 v[6:7], s[2:3], v158, s24, v[6:7]
	v_mul_u32_u24_e32 v0, 0x60, v147
	v_lshl_add_u64 v[8:9], v[114:115], 1, v[8:9]
	v_lshl_add_u64 v[14:15], v[116:117], 1, v[10:11]
	v_mad_i32_i24 v7, v159, s24, v7
	v_lshlrev_b32_e32 v0, 1, v0
	s_barrier
	global_load_dwordx4 v[10:13], v[8:9], off
	s_nop 0
	global_load_dwordx4 v[14:17], v[14:15], off
	v_lshl_add_u64 v[8:9], v[18:19], 0, v[124:125]
	v_lshl_add_u64 v[18:19], v[20:21], 0, v[126:127]
	v_mov_b32_e32 v145, v1
	v_lshl_add_u64 v[6:7], v[6:7], 0, v[0:1]
	v_lshl_add_u64 v[22:23], v[18:19], 0, v[144:145]
	v_lshl_add_u64 v[18:19], v[20:21], 0, v[128:129]
	v_lshl_add_u64 v[6:7], v[6:7], 0, v[112:113]
	v_mov_b32_e32 v143, v1
	v_lshl_add_u64 v[8:9], v[118:119], 1, v[8:9]
	v_lshl_add_u64 v[26:27], v[18:19], 0, v[144:145]
	v_lshl_add_u64 v[6:7], v[6:7], 0, v[142:143]
	global_load_dwordx4 v[18:21], v[8:9], off
	s_nop 0
	global_load_dwordx4 v[22:25], v[22:23], off
	s_nop 0
	global_load_dwordx4 v[26:29], v[26:27], off
	s_nop 0
	global_load_dwordx4 v[100:103], v[6:7], off
	global_load_dwordx4 v[96:99], v[6:7], off offset:32
	global_load_dwordx4 v[92:95], v[6:7], off offset:64
	global_load_dwordx4 v[88:91], v[6:7], off offset:96
	global_load_dwordx4 v[84:87], v[6:7], off offset:128
	global_load_dwordx4 v[80:83], v[6:7], off offset:160
	s_mov_b32 s2, 0x220000
	v_add_u32_e32 v38, 0x6800, v171
	v_add_u32_e32 v39, 0x7900, v171
	v_mad_i64_i32 v[30:31], s[2:3], v2, s2, v[134:135]
	v_mad_i64_i32 v[32:33], s[2:3], v2, s15, v[136:137]
	v_mad_i64_i32 v[34:35], s[2:3], v2, s15, v[138:139]
	v_mad_i64_i32 v[36:37], s[2:3], v2, s15, v[140:141]
	v_add_u32_e32 v177, 1, v5
	v_mov_b32_e32 v2, v1
	v_mov_b32_e32 v3, v1
	v_mov_b32_e32 v4, v1
	v_mov_b32_e32 v5, v1
	v_mov_b32_e32 v6, v1
	v_mov_b32_e32 v7, v1
	v_mov_b32_e32 v8, v1
	v_mov_b32_e32 v9, v1
	v_mad_u64_u32 v[160:161], s[6:7], v147, s14, v[30:31]
	v_mad_u64_u32 v[162:163], s[6:7], v147, s48, v[32:33]
	v_mad_u64_u32 v[164:165], s[6:7], v147, s48, v[34:35]
	v_mad_u64_u32 v[166:167], s[6:7], v147, s48, v[36:37]
	v_mov_b32_e32 v0, v1
	s_mov_b32 s2, 0
	v_mov_b32_e32 v143, 0
	v_mov_b32_e32 v145, 0xf149f2ca
	s_mov_b64 s[6:7], 0
	s_waitcnt vmcnt(10)
	ds_write_b128 v151, v[10:13]
	s_waitcnt vmcnt(9)
	ds_write_b128 v157, v[14:17]
	s_waitcnt vmcnt(8)
	ds_write_b128 v169, v[18:21]
	s_waitcnt vmcnt(7)
	ds_write2_b64 v38, v[22:23], v[24:25] offset1:1
	s_waitcnt vmcnt(6)
	ds_write2_b64 v39, v[26:27], v[28:29] offset1:1
	v_mov_b32_e32 v14, v1
	v_mov_b32_e32 v15, v1
	v_mov_b32_e32 v10, v1
	v_mov_b32_e32 v11, v1
	v_mov_b32_e32 v12, v1
	v_mov_b32_e32 v13, v1
	v_mov_b64_e32 v[30:31], v[14:15]
	v_mov_b64_e32 v[46:47], v[14:15]
	v_mov_b64_e32 v[28:29], v[12:13]
	v_mov_b64_e32 v[26:27], v[10:11]
	v_mov_b64_e32 v[24:25], v[8:9]
	v_mov_b64_e32 v[22:23], v[6:7]
	v_mov_b64_e32 v[20:21], v[4:5]
	v_mov_b64_e32 v[18:19], v[2:3]
	v_mov_b64_e32 v[16:17], v[0:1]
	v_mov_b64_e32 v[44:45], v[12:13]
	v_mov_b64_e32 v[42:43], v[10:11]
	v_mov_b64_e32 v[40:41], v[8:9]
	v_mov_b64_e32 v[38:39], v[6:7]
	v_mov_b64_e32 v[36:37], v[4:5]
	v_mov_b64_e32 v[34:35], v[2:3]
	v_mov_b64_e32 v[32:33], v[0:1]
	s_waitcnt lgkmcnt(0)
	s_barrier
	v_mov_b32_e32 v224, 0
	v_mov_b32_e32 v225, 0
	v_mov_b32_e32 v226, 0
	v_mov_b32_e32 v227, 0
	v_mov_b32_e32 v228, 0
	v_mov_b32_e32 v229, 0
	v_mov_b32_e32 v230, 0
	v_mov_b32_e32 v231, 0
	v_mov_b32_e32 v232, 0
	v_mov_b32_e32 v233, 0
	v_mov_b32_e32 v234, 0
	v_mov_b32_e32 v235, 0
	v_mov_b32_e32 v236, 0
	v_mov_b32_e32 v237, 0
	v_mov_b32_e32 v238, 0
	v_mov_b32_e32 v239, 0
	v_mov_b32_e32 v204, 0
	v_lshl_add_u64 v[162:163], s[96:97], 0, v[162:163]
	v_lshl_add_u64 v[166:167], s[96:97], 0, v[166:167]
	v_lshl_add_u64 v[164:165], s[96:97], 0, v[164:165]
	v_lshl_add_u64 v[160:161], s[96:97], 0, v[160:161]
	s_mov_b32 s8, 0x12323000
	s_mov_b32 s9, 0
	v_lshl_add_u64 v[164:165], s[8:9], 0, v[164:165]
	s_mov_b32 s8, 0x13ce4000
	v_lshl_add_u64 v[184:185], s[8:9], 0, v[160:161]
	s_mov_b32 s8, 0x13ca0000
	v_lshl_add_u64 v[160:161], s[8:9], 0, v[160:161]
	s_branch .LBB0_895
; #define MFMA(a, b, c) __builtin_amdgcn_mfma_f32_32x32x16_bf16((a), (b), (c), 0, 0, 0)
; DI unsigned pack2(float a, float b) { f32v2 v = {a, b}; return __builtin_bit_cast(unsigned, __builtin_convertvector(v, bf16v2)); }
; #define LSTORE(bf) { *(uint4*)&Ks[bf][kr0][kc0] = rk0; *(uint4*)&Ks[bf][kr1][kc1] = rk1; if (NKC == 3) *(uint4*)&Ks[bf][kr2][kc2] = rk2; \
;     *(uint2*)&Vs[bf][vd0][vk0] = make_uint2(rv0.x, rv0.y); *(uint2*)&Vs[bf][vd0][vk0 + 4] = make_uint2(rv0.z, rv0.w); \
;     *(uint2*)&Vs[bf][vd0 + 32][vk0] = make_uint2(rv1.x, rv1.y); *(uint2*)&Vs[bf][vd0 + 32][vk0 + 4] = make_uint2(rv1.z, rv1.w); }
; #define LSTORE(bf) { *(uint4*)&Ks[bf][kr0][kc0] = rk0; *(uint4*)&Ks[bf][kr1][kc1] = rk1; if (NKC == 3) *(uint4*)&Ks[bf][kr2][kc2] = rk2; \
;     *(uint2*)&Vs[bf][vd0][vk0] = make_uint2(rv0.x, rv0.y); *(uint2*)&Vs[bf][vd0][vk0 + 4] = make_uint2(rv0.z, rv0.w); \
;     *(uint2*)&Vs[bf][vd0 + 32][vk0] = make_uint2(rv1.x, rv1.y); *(uint2*)&Vs[bf][vd0 + 32][vk0 + 4] = make_uint2(rv1.z, rv1.w); }
; template <int DK, bool NA> ...
;     ...
;       float ls = 0.f;
; #pragma unroll
;       for (int kb = 0; kb < 2; kb++)
; #pragma unroll
;         for (int i = 0; i < 16; i++) { float pv = __builtin_amdgcn_exp2f(s[kb][i] - mn); s[kb][i] = pv; ls += pv; }
;       l_run += ls;
;       bf16x8 pf[2][2];
; #pragma unroll
;       for (int kb = 0; kb < 2; kb++)
; #pragma unroll
;         for (int sx = 0; sx < 2; sx++) {
;           uint4 u; u.x = pack2(s[kb][8 * sx], s[kb][8 * sx + 1]); u.y = pack2(s[kb][8 * sx + 2], s[kb][8 * sx + 3]);
;           u.z = pack2(s[kb][8 * sx + 4], s[kb][8 * sx + 5]); u.w = pack2(s[kb][8 * sx + 6], s[kb][8 * sx + 7]);
;           pf[kb][sx] = __builtin_bit_cast(bf16x8, u);
;         }
; #pragma unroll
;       for (int db = 0; db < 2; db++)
; #pragma unroll
;         for (int kb = 0; kb < 2; kb++)
; #pragma unroll
;           for (int sx = 0; sx < 2; sx++) {
;             const u16* vp = &Vs[buf][db * 32 + r][32 * kb + 16 * sx + 4 * h];
;             uint2 lo = *(const uint2*)vp, hi = *(const uint2*)(vp + 8);
;             uint4 u; u.x = lo.x; u.y = lo.y; u.z = hi.x; u.w = hi.y;
;             o[db] = MFMA(__builtin_bit_cast(bf16x8, u), pf[kb][sx], o[db]);
;           }
;     }
;     if (t + 1 < nTiles) LSTORE(buf ^ 1);
;     __syncthreads();
.LBB0_894:
	s_mul_i32 s8, s3, 0x2200
	v_add_u32_e32 v0, s8, v173
	v_add_u32_e32 v15, 0x6800, v0
	v_add_u32_e32 v0, 0x7800, v0
	ds_read2_b64 v[240:243], v15 offset0:0 offset1:2
	ds_read2_b64 v[244:247], v0 offset0:32 offset1:34
	ds_read2_b64 v[248:251], v15 offset0:4 offset1:6
	ds_read2_b64 v[178:181], v0 offset0:36 offset1:38
	v_exp_f32_e32 v64, v64
	v_exp_f32_e32 v65, v65
	v_exp_f32_e32 v66, v66
	v_exp_f32_e32 v67, v67
	v_exp_f32_e32 v68, v68
	v_exp_f32_e32 v69, v69
	v_exp_f32_e32 v70, v70
	v_exp_f32_e32 v71, v71
	v_cvt_pk_bf16_f32 v188, v64, v65
	v_cvt_pk_bf16_f32 v189, v66, v67
	v_cvt_pk_bf16_f32 v190, v68, v69
	v_cvt_pk_bf16_f32 v191, v70, v71
	v_add_f32_e32 v14, v64, v65
	v_add_f32_e32 v14, v66, v14
	v_add_f32_e32 v14, v67, v14
	v_add_f32_e32 v14, v68, v14
	v_add_f32_e32 v14, v69, v14
	v_add_f32_e32 v14, v70, v14
	v_add_f32_e32 v14, v71, v14
	ds_read2_b64 v[64:67], v15 offset0:8 offset1:10
	ds_read2_b64 v[68:71], v0 offset0:40 offset1:42
	s_waitcnt lgkmcnt(4)
	v_mfma_f32_32x32x16_bf16 v[32:47], v[240:243], v[188:191], v[32:47]
	v_exp_f32_e32 v72, v72
	v_exp_f32_e32 v73, v73
	v_exp_f32_e32 v74, v74
	v_exp_f32_e32 v75, v75
	v_exp_f32_e32 v76, v76
	v_exp_f32_e32 v77, v77
	v_exp_f32_e32 v78, v78
	v_exp_f32_e32 v79, v79
	v_cvt_pk_bf16_f32 v192, v72, v73
	v_cvt_pk_bf16_f32 v193, v74, v75
	v_mfma_f32_32x32x16_bf16 v[16:31], v[244:247], v[188:191], v[16:31]
	v_cvt_pk_bf16_f32 v194, v76, v77
	v_cvt_pk_bf16_f32 v195, v78, v79
	v_add_f32_e32 v14, v72, v14
	v_add_f32_e32 v14, v73, v14
	v_add_f32_e32 v14, v74, v14
	v_add_f32_e32 v14, v75, v14
	v_add_f32_e32 v14, v76, v14
	v_add_f32_e32 v14, v77, v14
	v_add_f32_e32 v14, v78, v14
	v_add_f32_e32 v14, v79, v14
	ds_read2_b64 v[72:75], v15 offset0:12 offset1:14
	ds_read2_b64 v[76:79], v0 offset0:44 offset1:46
	s_waitcnt lgkmcnt(4)
	v_mfma_f32_32x32x16_bf16 v[32:47], v[248:251], v[192:195], v[32:47]
	v_exp_f32_e32 v48, v48
	v_exp_f32_e32 v49, v49
	v_exp_f32_e32 v50, v50
	v_exp_f32_e32 v51, v51
	v_exp_f32_e32 v52, v52
	v_exp_f32_e32 v53, v53
	v_exp_f32_e32 v54, v54
	v_exp_f32_e32 v55, v55
	v_cvt_pk_bf16_f32 v196, v48, v49
	v_cvt_pk_bf16_f32 v197, v50, v51
	v_mfma_f32_32x32x16_bf16 v[16:31], v[178:181], v[192:195], v[16:31]
	v_cvt_pk_bf16_f32 v198, v52, v53
	v_cvt_pk_bf16_f32 v199, v54, v55
	v_add_f32_e32 v14, v48, v14
	v_add_f32_e32 v14, v49, v14
	v_add_f32_e32 v14, v50, v14
	v_add_f32_e32 v14, v51, v14
	v_add_f32_e32 v14, v52, v14
	v_add_f32_e32 v14, v53, v14
	v_add_f32_e32 v14, v54, v14
	v_add_f32_e32 v14, v55, v14
	s_waitcnt lgkmcnt(2)
	v_mfma_f32_32x32x16_bf16 v[32:47], v[64:67], v[196:199], v[32:47]
	v_exp_f32_e32 v56, v56
	v_exp_f32_e32 v57, v57
	v_exp_f32_e32 v58, v58
	v_exp_f32_e32 v59, v59
	v_exp_f32_e32 v60, v60
	v_exp_f32_e32 v61, v61
	v_exp_f32_e32 v62, v62
	v_exp_f32_e32 v63, v63
	v_cvt_pk_bf16_f32 v200, v56, v57
	v_cvt_pk_bf16_f32 v201, v58, v59
	v_mfma_f32_32x32x16_bf16 v[16:31], v[68:71], v[196:199], v[16:31]
	v_cvt_pk_bf16_f32 v202, v60, v61
	v_cvt_pk_bf16_f32 v203, v62, v63
	v_add_f32_e32 v14, v56, v14
	v_add_f32_e32 v14, v57, v14
	v_add_f32_e32 v14, v58, v14
	v_add_f32_e32 v14, v59, v14
	v_add_f32_e32 v14, v60, v14
	v_add_f32_e32 v14, v61, v14
	v_add_f32_e32 v14, v62, v14
	v_add_f32_e32 v14, v63, v14
	s_waitcnt lgkmcnt(0)
	v_mfma_f32_32x32x16_bf16 v[32:47], v[72:75], v[200:203], v[32:47]
	v_mfma_f32_32x32x16_bf16 v[16:31], v[76:79], v[200:203], v[16:31]
	v_add_f32_e32 v143, v143, v14
	s_xor_b32 s3, s3, 1
	s_mul_i32 s8, s3, 0x3400
	s_mulk_i32 s3, 0xee00
	s_add_i32 s2, s2, 1
	v_cmp_eq_u32_e32 vcc, s2, v177
	v_lshl_add_u64 v[162:163], v[162:163], 0, s[12:13]
	v_lshl_add_u64 v[164:165], v[164:165], 0, s[12:13]
	v_lshl_add_u64 v[166:167], v[166:167], 0, s[12:13]
	v_add3_u32 v0, s8, v149, v174
	s_waitcnt vmcnt(4)
	ds_write_b128 v0, v[2:5]
	v_add3_u32 v0, s8, v153, v175
	s_waitcnt vmcnt(3)
	ds_write_b128 v0, v[6:9]
	v_add3_u32 v0, s8, v168, v176
	s_add_i32 s8, s8, s3
	s_waitcnt vmcnt(2)
	ds_write_b128 v0, v[10:13]
	v_add3_u32 v0, s8, v170, v144
	s_mov_b64 s[8:9], 0x80
	v_add_u32_e32 v2, 0x6800, v0
	v_add_u32_e32 v0, 0x7900, v0
	v_lshl_add_u64 v[160:161], v[160:161], 0, s[8:9]
	v_lshl_add_u64 v[184:185], v[184:185], 0, s[8:9]
	s_or_b64 s[6:7], vcc, s[6:7]
	s_waitcnt vmcnt(0)
	ds_write2_b64 v2, v[104:105], v[106:107] offset1:1
	ds_write2_b64 v0, v[108:109], v[110:111] offset1:1
	s_waitcnt lgkmcnt(0)
	s_barrier
	s_andn2_b64 exec, exec, s[6:7]
	s_cbranch_execz .LBB0_897
; #define MFMA(a, b, c) __builtin_amdgcn_mfma_f32_32x32x16_bf16((a), (b), (c), 0, 0, 0)
; #define GLOAD(t) { const int pos0_ = TILE_POS(t); \
;     rk0 = *(const uint4*)(K + (size_t)(pos0_ + kr0) * ldk + kc0); rk1 = *(const uint4*)(K + (size_t)(pos0_ + kr1) * ldk + kc1); \
;     if (NKC == 3) rk2 = *(const uint4*)(K + (size_t)(pos0_ + kr2) * ldk + kc2); \
;     rv0 = *(const uint4*)(Vt + (size_t)vd0 * SEQA + pos0_ + vk0); rv1 = *(const uint4*)(Vt + (size_t)(vd0 + 32) * SEQA + pos0_ + vk0); }
; #define GLOAD(t) { const int pos0_ = (t) * 64; \
;     rk0 = *(const uint4*)(K + (size_t)(pos0_ + kr0) * ldk + kc0); rk1 = *(const uint4*)(K + (size_t)(pos0_ + kr1) * ldk + kc1); \
;     if (NKC == 3) rk2 = *(const uint4*)(K + (size_t)(pos0_ + kr2) * ldk + kc2); \
;     rv0 = *(const uint4*)(Vt + (size_t)vd0 * SEQA + pos0_ + vk0); rv1 = *(const uint4*)(Vt + (size_t)(vd0 + 32) * SEQA + pos0_ + vk0); }
; template <int DK, bool NA> ...
;     ...
;   for (int t = 0; t < nTiles; t++) {
;     const int buf = t & 1;
;     if (t + 1 < nTiles) GLOAD(t + 1);
;     const bool win = NA && (t < nWin);
;     const int kr = rsA + t;
;     bool act = true;
;     if (win) act = (kr >= rsw) && (kr < rsw + 8);
;     if (act) {
;       f32x16 s[2];
; #pragma unroll
;       for (int kb = 0; kb < 2; kb++) {
; #pragma unroll
;         for (int i = 0; i < 16; i++) s[kb][i] = 0.f;
; #pragma unroll
;         for (int ks = 0; ks < KS; ks++) { bf16x8 a = *(const bf16x8*)&Ks[buf][kb * 32 + r][ks * 16 + h * 8]; s[kb] = MFMA(a, qf[ks], s[kb]); }
.LBB0_895:
	s_and_b32 s3, s2, 1
	s_mul_i32 s8, s3, 0x3400
	v_add_u32_e32 v0, s8, v172
	global_load_dwordx4 v[2:5], v[162:163], off
	global_load_dwordx4 v[6:9], v[166:167], off
	global_load_dwordx4 v[10:13], v[164:165], off
	global_load_dwordx4 v[108:111], v[184:185], off offset:128
	global_load_dwordx4 v[104:107], v[160:161], off offset:128
	ds_read_b128 v[48:51], v0
	ds_read_b128 v[52:55], v0 offset:32
	s_waitcnt vmcnt(10) lgkmcnt(1)
	v_mfma_f32_32x32x16_bf16 v[64:79], v[48:51], v[100:103], v[224:239]
	ds_read_b128 v[48:51], v0 offset:64
	ds_read_b128 v[178:181], v0 offset:6688
	s_waitcnt vmcnt(9) lgkmcnt(2)
	v_mfma_f32_32x32x16_bf16 v[64:79], v[52:55], v[96:99], v[64:79]
	s_waitcnt vmcnt(8) lgkmcnt(1)
	v_mfma_f32_32x32x16_bf16 v[64:79], v[48:51], v[92:95], v[64:79]
	ds_read_b128 v[48:51], v0 offset:96
	s_waitcnt vmcnt(7) lgkmcnt(0)
	v_mfma_f32_32x32x16_bf16 v[64:79], v[48:51], v[88:91], v[64:79]
	ds_read_b128 v[48:51], v0 offset:128
	s_waitcnt vmcnt(6) lgkmcnt(0)
	v_mfma_f32_32x32x16_bf16 v[64:79], v[48:51], v[84:87], v[64:79]
	ds_read_b128 v[48:51], v0 offset:160
	s_waitcnt vmcnt(5) lgkmcnt(0)
	v_mfma_f32_32x32x16_bf16 v[64:79], v[48:51], v[80:83], v[64:79]
	ds_read_b128 v[48:51], v0 offset:6656
	s_waitcnt lgkmcnt(0)
	v_mfma_f32_32x32x16_bf16 v[48:63], v[48:51], v[100:103], v[224:239]
	v_mfma_f32_32x32x16_bf16 v[48:63], v[178:181], v[96:99], v[48:63]
	ds_read_b128 v[178:181], v0 offset:6720
	s_waitcnt lgkmcnt(0)
	v_mfma_f32_32x32x16_bf16 v[48:63], v[178:181], v[92:95], v[48:63]
	ds_read_b128 v[178:181], v0 offset:6752
	s_waitcnt lgkmcnt(0)
	v_mfma_f32_32x32x16_bf16 v[48:63], v[178:181], v[88:91], v[48:63]
	ds_read_b128 v[178:181], v0 offset:6784
	s_waitcnt lgkmcnt(0)
	v_mfma_f32_32x32x16_bf16 v[48:63], v[178:181], v[84:87], v[48:63]
	ds_read_b128 v[178:181], v0 offset:6816
	v_max3_f32 v0, v64, s16, v65
	v_max3_f32 v0, v0, v66, v67
	v_max3_f32 v0, v0, v68, v69
	v_max3_f32 v0, v0, v70, v71
	v_max3_f32 v0, v0, v72, v73
	v_max3_f32 v0, v0, v74, v75
	s_waitcnt lgkmcnt(0)
	v_mfma_f32_32x32x16_bf16 v[48:63], v[178:181], v[80:83], v[48:63]
	v_max3_f32 v0, v0, v76, v77
	v_max3_f32 v0, v0, v78, v79
	s_nop 9
	v_max3_f32 v0, v0, v48, v49
	v_max3_f32 v0, v0, v50, v51
	v_max3_f32 v0, v0, v52, v53
	v_max3_f32 v0, v0, v54, v55
	v_max3_f32 v0, v0, v56, v57
	v_max3_f32 v0, v0, v58, v59
	v_max3_f32 v0, v0, v60, v61
	v_max3_f32 v0, v0, v62, v63
	v_mov_b32_e32 v14, v0
	s_nop 1
	v_permlane32_swap_b32_e32 v0, v14
	v_max_f32_e32 v14, v14, v14
	v_max_f32_e32 v0, v0, v0
	v_max_f32_e32 v0, v0, v14
	v_add_f32_e32 v0, v0, v204
	v_add_f32_e32 v14, 4.0, v145
	v_cmp_gt_f32_e32 vcc, v0, v14
	s_cbranch_vccz .LBB0_894
	v_max_f32_e32 v0, v0, v0
	v_max_f32_e32 v14, v145, v145
	v_max_f32_e32 v14, v14, v0
	v_sub_f32_e32 v0, v145, v14
	v_exp_f32_e32 v0, v0
	v_mov_b32_e32 v145, v14
	v_sub_f32_e32 v15, v14, v204
	v_mov_b32_e32 v204, v14
	v_sub_f32_e32 v224, 0, v14
	v_mov_b32_e32 v225, v224
	v_mov_b32_e32 v226, v224
	v_mov_b32_e32 v227, v224
	v_mov_b32_e32 v228, v224
	v_mov_b32_e32 v229, v224
	v_mov_b32_e32 v230, v224
	v_mov_b32_e32 v231, v224
	v_mov_b32_e32 v232, v224
	v_mov_b32_e32 v233, v224
	v_mov_b32_e32 v234, v224
	v_mov_b32_e32 v235, v224
	v_mov_b32_e32 v236, v224
	v_mov_b32_e32 v237, v224
	v_mov_b32_e32 v238, v224
	v_mov_b32_e32 v239, v224
	v_sub_f32_e32 v64, v64, v15
	v_sub_f32_e32 v65, v65, v15
	v_sub_f32_e32 v66, v66, v15
	v_sub_f32_e32 v67, v67, v15
	v_sub_f32_e32 v68, v68, v15
	v_sub_f32_e32 v69, v69, v15
	v_sub_f32_e32 v70, v70, v15
	v_sub_f32_e32 v71, v71, v15
	v_sub_f32_e32 v72, v72, v15
	v_sub_f32_e32 v73, v73, v15
	v_sub_f32_e32 v74, v74, v15
	v_sub_f32_e32 v75, v75, v15
	v_sub_f32_e32 v76, v76, v15
	v_sub_f32_e32 v77, v77, v15
	v_sub_f32_e32 v78, v78, v15
	v_sub_f32_e32 v79, v79, v15
	v_sub_f32_e32 v48, v48, v15
	v_sub_f32_e32 v49, v49, v15
	v_sub_f32_e32 v50, v50, v15
	v_sub_f32_e32 v51, v51, v15
	v_sub_f32_e32 v52, v52, v15
	v_sub_f32_e32 v53, v53, v15
	v_sub_f32_e32 v54, v54, v15
	v_sub_f32_e32 v55, v55, v15
	v_sub_f32_e32 v56, v56, v15
	v_sub_f32_e32 v57, v57, v15
	v_sub_f32_e32 v58, v58, v15
	v_sub_f32_e32 v59, v59, v15
	v_sub_f32_e32 v60, v60, v15
	v_sub_f32_e32 v61, v61, v15
	v_sub_f32_e32 v62, v62, v15
	v_sub_f32_e32 v63, v63, v15
	v_pk_mul_f32 v[46:47], v[46:47], v[0:1] op_sel_hi:[1,0]
	v_pk_mul_f32 v[44:45], v[44:45], v[0:1] op_sel_hi:[1,0]
	v_pk_mul_f32 v[42:43], v[42:43], v[0:1] op_sel_hi:[1,0]
	v_pk_mul_f32 v[40:41], v[40:41], v[0:1] op_sel_hi:[1,0]
	v_pk_mul_f32 v[38:39], v[38:39], v[0:1] op_sel_hi:[1,0]
	v_pk_mul_f32 v[36:37], v[36:37], v[0:1] op_sel_hi:[1,0]
	v_pk_mul_f32 v[34:35], v[34:35], v[0:1] op_sel_hi:[1,0]
	v_pk_mul_f32 v[32:33], v[32:33], v[0:1] op_sel_hi:[1,0]
	v_pk_mul_f32 v[30:31], v[30:31], v[0:1] op_sel_hi:[1,0]
	v_pk_mul_f32 v[28:29], v[28:29], v[0:1] op_sel_hi:[1,0]
	v_pk_mul_f32 v[26:27], v[26:27], v[0:1] op_sel_hi:[1,0]
	v_pk_mul_f32 v[24:25], v[24:25], v[0:1] op_sel_hi:[1,0]
	v_pk_mul_f32 v[22:23], v[22:23], v[0:1] op_sel_hi:[1,0]
	v_pk_mul_f32 v[20:21], v[20:21], v[0:1] op_sel_hi:[1,0]
	v_pk_mul_f32 v[18:19], v[18:19], v[0:1] op_sel_hi:[1,0]
	v_pk_mul_f32 v[16:17], v[16:17], v[0:1] op_sel_hi:[1,0]
	v_mul_f32_e32 v143, v143, v0
	s_branch .LBB0_894
